# adds prologue: p->bf16 loop 8 loads in flight; x->H/XU row loop issues all 8 row-chunk loads together and keeps the norm gains in registers
# speedup vs baseline: 1.0051x; 1.0033x over previous
; __device__ __forceinline__ unsigned pk2(float lo, float hi) { return pg8::cvt_pk_bf16(lo, hi); }
; __device__ __forceinline__ void prologue(const Params& P, LAS unsigned char* L, int gw, int NGW, int wave, int lane, int nitems) {
;     ...
;       const f32x4* ps = (const f32x4*)P.p; v2u* pd = (v2u*)(ws + WS_PBF);
;       for (int i = gt; i < DEPTH * M * PLE / 4; i += NT) { const f32x4 v = ps[i]; v2u o; o.x = pk2(v[0], v[1]); o.y = pk2(v[2], v[3]); pd[i] = o; }
.Lp8_check:
	v_add_u32_e32 v5, s36, v4
	v_add_u32_e32 v5, s36, v5
	v_add_u32_e32 v5, s36, v5
	v_add_u32_e32 v5, s36, v5
	v_add_u32_e32 v5, s36, v5
	v_add_u32_e32 v5, s36, v5
	v_add_u32_e32 v5, s36, v5
	v_cmp_ge_i32_e32 vcc, s5, v5
	s_and_b64 vcc, vcc, exec
	s_cmp_eq_u64 vcc, exec
	s_cbranch_scc0 .Lp8_rem
	global_load_dwordx4 v[6:9], v[0:1], off
	v_lshl_add_u64 v[0:1], v[0:1], 0, s[6:7]
	global_load_dwordx4 v[14:17], v[0:1], off
	v_lshl_add_u64 v[0:1], v[0:1], 0, s[6:7]
	global_load_dwordx4 v[18:21], v[0:1], off
	v_lshl_add_u64 v[0:1], v[0:1], 0, s[6:7]
	global_load_dwordx4 v[22:25], v[0:1], off
	v_lshl_add_u64 v[0:1], v[0:1], 0, s[6:7]
	global_load_dwordx4 v[26:29], v[0:1], off
	v_lshl_add_u64 v[0:1], v[0:1], 0, s[6:7]
	global_load_dwordx4 v[52:55], v[0:1], off
	v_lshl_add_u64 v[0:1], v[0:1], 0, s[6:7]
	global_load_dwordx4 v[56:59], v[0:1], off
	v_lshl_add_u64 v[0:1], v[0:1], 0, s[6:7]
	global_load_dwordx4 v[60:63], v[0:1], off
	v_lshl_add_u64 v[0:1], v[0:1], 0, s[6:7]
	v_add_u32_e32 v4, s36, v5
	s_waitcnt vmcnt(7)
	v_cvt_pk_bf16_f32 v6, v6, v7
	v_cvt_pk_bf16_f32 v7, v8, v9
	global_store_dwordx2 v[2:3], v[6:7], off
	v_lshl_add_u64 v[2:3], v[2:3], 0, s[8:9]
	s_waitcnt vmcnt(7)
	v_cvt_pk_bf16_f32 v14, v14, v15
	v_cvt_pk_bf16_f32 v15, v16, v17
	global_store_dwordx2 v[2:3], v[14:15], off
	v_lshl_add_u64 v[2:3], v[2:3], 0, s[8:9]
	s_waitcnt vmcnt(7)
	v_cvt_pk_bf16_f32 v18, v18, v19
	v_cvt_pk_bf16_f32 v19, v20, v21
	global_store_dwordx2 v[2:3], v[18:19], off
	v_lshl_add_u64 v[2:3], v[2:3], 0, s[8:9]
	s_waitcnt vmcnt(7)
	v_cvt_pk_bf16_f32 v22, v22, v23
	v_cvt_pk_bf16_f32 v23, v24, v25
	global_store_dwordx2 v[2:3], v[22:23], off
	v_lshl_add_u64 v[2:3], v[2:3], 0, s[8:9]
	s_waitcnt vmcnt(7)
	v_cvt_pk_bf16_f32 v26, v26, v27
	v_cvt_pk_bf16_f32 v27, v28, v29
	global_store_dwordx2 v[2:3], v[26:27], off
	v_lshl_add_u64 v[2:3], v[2:3], 0, s[8:9]
	s_waitcnt vmcnt(7)
	v_cvt_pk_bf16_f32 v52, v52, v53
	v_cvt_pk_bf16_f32 v53, v54, v55
	global_store_dwordx2 v[2:3], v[52:53], off
	v_lshl_add_u64 v[2:3], v[2:3], 0, s[8:9]
	s_waitcnt vmcnt(7)
	v_cvt_pk_bf16_f32 v56, v56, v57
	v_cvt_pk_bf16_f32 v57, v58, v59
	global_store_dwordx2 v[2:3], v[56:57], off
	v_lshl_add_u64 v[2:3], v[2:3], 0, s[8:9]
	s_waitcnt vmcnt(7)
	v_cvt_pk_bf16_f32 v60, v60, v61
	v_cvt_pk_bf16_f32 v61, v62, v63
	global_store_dwordx2 v[2:3], v[60:61], off
	v_lshl_add_u64 v[2:3], v[2:3], 0, s[8:9]
	s_branch .Lp8_check
.Lp8_rem:
	v_cmp_ge_i32_e32 vcc, s5, v4
	s_and_b64 exec, exec, vcc
	s_cbranch_execz .LBB0_154

; __device__ __forceinline__ void rmsnorm_row_copy_bf16(const float* xrow, const float* g, pg8::h16_t* hrow, bf16* orow, int lane) {
;     const f32x4* xr = (const f32x4*)xrow + lane; pg8::h16x4* hr = (pg8::h16x4*)hrow + lane; f32x4 v[8]; float s = 0.f;
; #pragma unroll
;     for (int j = 0; j < 8; ++j) { v[j] = xr[64 * j]; hr[64 * j] = __builtin_convertvector(v[j], pg8::h16x4); s += (v[j][0] * v[j][0] + v[j][1] * v[j][1]) + (v[j][2] * v[j][2] + v[j][3] * v[j][3]); }
; __device__ __forceinline__ void prologue(const Params& P, LAS unsigned char* L, int gw, int NGW, int wave, int lane, int nitems) {
;     ...
;       for (int row = gw; row < M; row += NGW) rmsnorm_row_copy_bf16(P.x + (size_t)row * D, P.norm_mix, (pg8::h16_t*)(ws + WS_H) + (size_t)row * D, (bf16*)(ws + WS_XU) + (size_t)row * D, lane);
.LBB0_154:
	s_or_b64 exec, exec, s[0:1]
	s_cmpk_gt_i32 s4, 0x1fff
	s_waitcnt vmcnt(51)
	v_mbcnt_lo_u32_b32 v48, -1, 0
	s_cbranch_scc1 .LBB0_157
	v_mbcnt_hi_u32_b32 v0, -1, v48
	v_and_b32_e32 v1, 64, v0
	v_add_u32_e32 v1, 64, v1
	v_xor_b32_e32 v2, 1, v0
	v_cmp_lt_i32_e32 vcc, v2, v1
	s_mov_b64 s[6:7], 0x1400
	s_ashr_i32 s5, s4, 31
	v_cndmask_b32_e32 v2, v0, v2, vcc
	s_waitcnt vmcnt(50)
	v_lshlrev_b32_e32 v49, 2, v2
	v_xor_b32_e32 v2, 2, v0
	v_cmp_lt_i32_e32 vcc, v2, v1
	s_mov_b64 s[0:1], 0x1000
	s_waitcnt vmcnt(44)
	v_mov_b32_e32 v55, 0x358637bd
	v_cndmask_b32_e32 v2, v0, v2, vcc
	v_lshlrev_b32_e32 v50, 2, v2
	v_xor_b32_e32 v2, 4, v0
	v_cmp_lt_i32_e32 vcc, v2, v1
	s_waitcnt vmcnt(43)
	v_mov_b32_e32 v56, 0x260
	s_mov_b32 s10, 0xb100000
	v_cndmask_b32_e32 v2, v0, v2, vcc
	v_lshlrev_b32_e32 v51, 2, v2
	v_xor_b32_e32 v2, 8, v0
	v_cmp_lt_i32_e32 vcc, v2, v1
	s_nop 1
	v_cndmask_b32_e32 v2, v0, v2, vcc
	v_lshlrev_b32_e32 v52, 2, v2
	v_xor_b32_e32 v2, 16, v0
	v_cmp_lt_i32_e32 vcc, v2, v1
	s_nop 1
	v_cndmask_b32_e32 v2, v0, v2, vcc
	v_lshlrev_b32_e32 v53, 2, v2
	v_xor_b32_e32 v2, 32, v0
	v_cmp_lt_i32_e32 vcc, v2, v1
	v_mov_b32_e32 v1, 0
	s_nop 0
	v_cndmask_b32_e32 v0, v0, v2, vcc
	v_lshlrev_b32_e32 v54, 2, v0
	v_lshlrev_b32_e32 v0, 4, v12
	v_lshl_add_u64 v[34:35], s[44:45], 0, v[0:1]
	v_lshl_add_u64 v[38:39], v[34:35], 0, s[6:7]
	s_mov_b64 s[6:7], 0x1800
	v_lshl_add_u64 v[40:41], v[34:35], 0, s[6:7]
	s_mov_b64 s[6:7], 0x1c00
	v_lshl_add_u64 v[42:43], v[34:35], 0, s[6:7]
	s_lshl_b64 s[6:7], s[4:5], 13
	s_add_u32 s6, s40, s6
	s_addc_u32 s7, s41, s7
	v_lshl_add_u64 v[2:3], s[6:7], 0, v[0:1]
	s_ashr_i32 s61, s60, 31
	v_lshl_add_u64 v[36:37], v[34:35], 0, s[0:1]
	v_lshl_add_u64 v[44:45], v[2:3], 0, s[0:1]
	s_lshl_b64 s[6:7], s[60:61], 13
	s_lshl_b64 s[0:1], s[4:5], 12
	s_add_u32 s0, s34, s0
	v_lshlrev_b32_e32 v0, 3, v12
	s_addc_u32 s1, s35, s1
	v_lshl_add_u64 v[0:1], s[0:1], 0, v[0:1]
	s_mov_b64 s[0:1], 0x51500000
	v_lshl_add_u64 v[46:47], v[0:1], 0, s[0:1]
	s_lshl_b64 s[8:9], s[60:61], 12
	s_mov_b32 s5, 0xf800000
	global_load_dwordx4 v[84:87], v[34:35], off
	global_load_dwordx4 v[88:91], v[34:35], off offset:1024
	global_load_dwordx4 v[92:95], v[34:35], off offset:2048
	global_load_dwordx4 v[96:99], v[34:35], off offset:3072
	global_load_dwordx4 v[100:103], v[36:37], off
	global_load_dwordx4 v[104:107], v[38:39], off
	global_load_dwordx4 v[108:111], v[40:41], off
	global_load_dwordx4 v[112:115], v[42:43], off
.LBB0_156:
	global_load_dwordx4 v[8:11], v[44:45], off offset:-4096
	global_load_dwordx4 v[0:3], v[44:45], off offset:-3072
	global_load_dwordx4 v[16:19], v[44:45], off offset:-2048
	global_load_dwordx4 v[20:23], v[44:45], off offset:-1024
	global_load_dwordx4 v[12:15], v[44:45], off
	global_load_dwordx4 v[24:27], v[44:45], off offset:1024
	global_load_dwordx4 v[28:31], v[44:45], off offset:2048
	global_load_dwordx4 v[4:7], v[44:45], off offset:3072
	s_nop 0
	v_add_co_u32_e32 v62, vcc, s10, v46
	s_add_i32 s4, s4, s60
	s_nop 0
	v_addc_co_u32_e32 v63, vcc, 0, v47, vcc
	s_cmpk_gt_i32 s4, 0x1fff
	s_waitcnt vmcnt(7)
	v_cvt_pk_f16_f32 v117, v10, v11
	v_cvt_pk_f16_f32 v116, v8, v9
	global_store_dwordx2 v[46:47], v[116:117], off
	v_mov_b32_e32 v60, v9
	v_mov_b32_e32 v66, v11
	v_mov_b32_e32 v58, v8
	v_mov_b32_e32 v64, v10
	s_waitcnt vmcnt(7)
	v_cvt_pk_f16_f32 v117, v2, v3
	v_cvt_pk_f16_f32 v116, v0, v1
	global_store_dwordx2 v[46:47], v[116:117], off offset:512
	v_mov_b32_e32 v61, v1
	v_mov_b32_e32 v67, v3
	v_mov_b32_e32 v59, v0
	v_mov_b32_e32 v65, v2
	v_pk_mul_f32 v[60:61], v[60:61], v[60:61]
	v_pk_mul_f32 v[66:67], v[66:67], v[66:67]
	v_pk_fma_f32 v[58:59], v[58:59], v[58:59], v[60:61]
	v_pk_fma_f32 v[60:61], v[64:65], v[64:65], v[66:67]
	s_waitcnt vmcnt(7)
	v_cvt_pk_f16_f32 v117, v18, v19
	v_cvt_pk_f16_f32 v116, v16, v17
	global_store_dwordx2 v[46:47], v[116:117], off offset:1024
	v_pk_add_f32 v[58:59], v[58:59], v[60:61]
	v_pk_mul_f32 v[60:61], v[18:19], v[18:19]
	v_pk_mul_f32 v[64:65], v[16:17], v[16:17]
	v_pk_add_f32 v[58:59], v[58:59], v[58:59] op_sel:[0,1] op_sel_hi:[1,0]
	v_pk_mov_b32 v[66:67], v[64:65], v[60:61] op_sel:[1,0]
	v_mov_b32_e32 v65, v61
	v_pk_add_f32 v[60:61], v[66:67], v[64:65]
	s_waitcnt vmcnt(7)
	v_cvt_pk_f16_f32 v117, v22, v23
	v_cvt_pk_f16_f32 v116, v20, v21
	global_store_dwordx2 v[46:47], v[116:117], off offset:1536
	v_mul_f32_e32 v64, v21, v21
	v_mul_f32_e32 v66, v23, v23
	v_pk_add_f32 v[60:61], v[60:61], v[60:61] op_sel:[0,1] op_sel_hi:[1,0]
	v_pk_fma_f32 v[64:65], v[20:21], v[20:21], v[64:65] op_sel_hi:[1,1,0]
	v_pk_fma_f32 v[66:67], v[22:23], v[22:23], v[66:67] op_sel_hi:[1,1,0]
	s_waitcnt vmcnt(7)
	v_cvt_pk_f16_f32 v117, v14, v15
	v_cvt_pk_f16_f32 v116, v12, v13
	global_store_dwordx2 v[46:47], v[116:117], off offset:2048
	v_mul_f32_e32 v59, v12, v12
	v_mul_f32_e32 v61, v13, v13
	v_mul_f32_e32 v65, v14, v14
	v_mul_f32_e32 v67, v15, v15
	v_pk_add_f32 v[58:59], v[58:59], v[60:61]
	v_pk_add_f32 v[60:61], v[64:65], v[66:67]
	s_waitcnt vmcnt(7)
	v_cvt_pk_f16_f32 v117, v26, v27
	v_cvt_pk_f16_f32 v116, v24, v25
	global_store_dwordx2 v[46:47], v[116:117], off offset:2560
	v_pk_add_f32 v[58:59], v[58:59], v[60:61]
	v_pk_mul_f32 v[60:61], v[24:25], v[24:25]
	v_pk_add_f32 v[64:65], v[58:59], v[58:59] op_sel:[0,1] op_sel_hi:[1,0]
	v_pk_mul_f32 v[58:59], v[26:27], v[26:27]
	s_waitcnt vmcnt(7)
; __device__ __forceinline__ unsigned pk2(float lo, float hi) { return pg8::cvt_pk_bf16(lo, hi); }
; __device__ __forceinline__ void rmsnorm_row_copy_bf16(const float* xrow, const float* g, pg8::h16_t* hrow, bf16* orow, int lane) {
;     ...
;     for (int j = 0; j < 8; ++j) { v[j] = xr[64 * j]; hr[64 * j] = __builtin_convertvector(v[j], pg8::h16x4); s += (v[j][0] * v[j][0] + v[j][1] * v[j][1]) + (v[j][2] * v[j][2] + v[j][3] * v[j][3]); }
;     const float rs = 1.0f / sqrtf(wave_sum(s) * (1.0f / D) + EPS);
;     const f32x4* gr = (const f32x4*)g + lane; v2u* o8 = (v2u*)orow + lane;
; #pragma unroll
;     for (int j = 0; j < 8; ++j) { const f32x4 gv = gr[64 * j]; v2u o; o.x = pk2(v[j][0] * rs * gv[0], v[j][1] * rs * gv[1]); o.y = pk2(v[j][2] * rs * gv[2], v[j][3] * rs * gv[3]); o8[64 * j] = o; }
	v_cvt_pk_f16_f32 v117, v30, v31
	v_cvt_pk_f16_f32 v116, v28, v29
	global_store_dwordx2 v[46:47], v[116:117], off offset:3072
	v_pk_mov_b32 v[66:67], v[60:61], v[58:59] op_sel:[1,0]
	v_mov_b32_e32 v61, v59
	v_pk_add_f32 v[58:59], v[66:67], v[60:61]
	v_mul_f32_e32 v60, v31, v31
	v_pk_add_f32 v[66:67], v[58:59], v[58:59] op_sel:[0,1] op_sel_hi:[1,0]
	v_mul_f32_e32 v58, v29, v29
	v_pk_fma_f32 v[68:69], v[28:29], v[28:29], v[58:59] op_sel_hi:[1,1,0]
	v_pk_fma_f32 v[70:71], v[30:31], v[30:31], v[60:61] op_sel_hi:[1,1,0]
	v_lshl_add_u64 v[44:45], v[44:45], 0, s[6:7]
	s_waitcnt vmcnt(7)
	v_cvt_pk_f16_f32 v117, v6, v7
	v_cvt_pk_f16_f32 v116, v4, v5
	global_store_dwordx2 v[46:47], v[116:117], off offset:3584
	v_mul_f32_e32 v65, v4, v4
	v_mul_f32_e32 v67, v5, v5
	v_mul_f32_e32 v69, v6, v6
	v_mul_f32_e32 v71, v7, v7
	v_pk_add_f32 v[64:65], v[64:65], v[66:67]
	v_pk_add_f32 v[66:67], v[68:69], v[70:71]
	v_lshl_add_u64 v[46:47], v[46:47], 0, s[8:9]
	v_pk_add_f32 v[64:65], v[64:65], v[66:67]
	s_nop 0
	v_add_f32_e32 v57, v64, v65
	ds_bpermute_b32 v64, v49, v57
	s_waitcnt lgkmcnt(0)
	v_add_f32_e32 v57, v57, v64
	ds_bpermute_b32 v64, v50, v57
	s_waitcnt lgkmcnt(0)
	v_add_f32_e32 v57, v57, v64
	ds_bpermute_b32 v64, v51, v57
	s_waitcnt lgkmcnt(0)
	v_add_f32_e32 v57, v57, v64
	ds_bpermute_b32 v64, v52, v57
	s_waitcnt lgkmcnt(0)
	v_add_f32_e32 v57, v57, v64
	ds_bpermute_b32 v64, v53, v57
	s_waitcnt lgkmcnt(0)
	v_add_f32_e32 v57, v57, v64
	ds_bpermute_b32 v64, v54, v57
	s_waitcnt lgkmcnt(0)
	v_add_f32_e32 v57, v57, v64
	v_fmamk_f32 v57, v57, 0x3a000000, v55
	v_mul_f32_e32 v64, 0x4f800000, v57
	v_cmp_gt_f32_e32 vcc, s5, v57
	s_nop 1
	v_cndmask_b32_e32 v57, v57, v64, vcc
	v_sqrt_f32_e32 v64, v57
	s_nop 0
	v_add_u32_e32 v65, -1, v64
	v_add_u32_e32 v66, 1, v64
	v_fma_f32 v67, -v65, v64, v57
	v_fma_f32 v68, -v66, v64, v57
	v_cmp_ge_f32_e64 s[0:1], 0, v67
	s_nop 1
	v_cndmask_b32_e64 v64, v64, v65, s[0:1]
	v_cmp_lt_f32_e64 s[0:1], 0, v68
	s_nop 1
	v_cndmask_b32_e64 v64, v64, v66, s[0:1]
	v_mul_f32_e32 v65, 0x37800000, v64
	v_cndmask_b32_e32 v64, v64, v65, vcc
	v_cmp_class_f32_e32 vcc, v57, v56
	s_nop 1
	v_cndmask_b32_e32 v57, v64, v57, vcc
	v_div_scale_f32 v64, s[0:1], v57, v57, 1.0
	v_rcp_f32_e32 v66, v64
	v_div_scale_f32 v65, vcc, 1.0, v57, 1.0
	v_fma_f32 v67, -v64, v66, 1.0
	v_fmac_f32_e32 v66, v67, v66
	v_mul_f32_e32 v67, v65, v66
	v_fma_f32 v68, -v64, v67, v65
	v_fmac_f32_e32 v67, v68, v66
	v_fma_f32 v64, -v64, v67, v65
	v_div_fmas_f32 v64, v64, v66, v67
	v_div_fixup_f32 v64, v64, v57, 1.0
	v_pk_mul_f32 v[8:9], v[8:9], v[64:65] op_sel_hi:[1,0]
	v_pk_mul_f32 v[10:11], v[10:11], v[64:65] op_sel_hi:[1,0]
	v_pk_mul_f32 v[8:9], v[84:85], v[8:9]
	v_pk_mul_f32 v[10:11], v[86:87], v[10:11]
	v_cvt_pk_bf16_f32 v8, v8, v9
	v_cvt_pk_bf16_f32 v9, v10, v11
	global_store_dwordx2 v[62:63], v[8:9], off
	v_pk_mul_f32 v[0:1], v[0:1], v[64:65] op_sel_hi:[1,0]
	v_pk_mul_f32 v[2:3], v[2:3], v[64:65] op_sel_hi:[1,0]
	v_pk_mul_f32 v[4:5], v[4:5], v[64:65] op_sel_hi:[1,0]
	v_pk_mul_f32 v[6:7], v[6:7], v[64:65] op_sel_hi:[1,0]
	v_pk_mul_f32 v[0:1], v[88:89], v[0:1]
	v_pk_mul_f32 v[2:3], v[90:91], v[2:3]
	v_cvt_pk_bf16_f32 v0, v0, v1
	v_cvt_pk_bf16_f32 v1, v2, v3
	global_store_dwordx2 v[62:63], v[0:1], off offset:512
	v_pk_mul_f32 v[8:9], v[16:17], v[64:65] op_sel_hi:[1,0]
	v_pk_mul_f32 v[10:11], v[18:19], v[64:65] op_sel_hi:[1,0]
	v_pk_mul_f32 v[0:1], v[92:93], v[8:9]
	v_pk_mul_f32 v[2:3], v[94:95], v[10:11]
	v_cvt_pk_bf16_f32 v0, v0, v1
	v_cvt_pk_bf16_f32 v1, v2, v3
	global_store_dwordx2 v[62:63], v[0:1], off offset:1024
	v_pk_mul_f32 v[8:9], v[20:21], v[64:65] op_sel_hi:[1,0]
	v_pk_mul_f32 v[10:11], v[22:23], v[64:65] op_sel_hi:[1,0]
	v_pk_mul_f32 v[0:1], v[96:97], v[8:9]
	v_pk_mul_f32 v[2:3], v[98:99], v[10:11]
	v_cvt_pk_bf16_f32 v0, v0, v1
	v_cvt_pk_bf16_f32 v1, v2, v3
	global_store_dwordx2 v[62:63], v[0:1], off offset:1536
	v_pk_mul_f32 v[8:9], v[12:13], v[64:65] op_sel_hi:[1,0]
	v_pk_mul_f32 v[10:11], v[14:15], v[64:65] op_sel_hi:[1,0]
	v_pk_mul_f32 v[0:1], v[8:9], v[100:101]
	v_pk_mul_f32 v[2:3], v[10:11], v[102:103]
	v_cvt_pk_bf16_f32 v0, v0, v1
	v_cvt_pk_bf16_f32 v1, v2, v3
	global_store_dwordx2 v[62:63], v[0:1], off offset:2048
	v_pk_mul_f32 v[8:9], v[24:25], v[64:65] op_sel_hi:[1,0]
	v_pk_mul_f32 v[10:11], v[26:27], v[64:65] op_sel_hi:[1,0]
	v_pk_mul_f32 v[0:1], v[8:9], v[104:105]
	v_pk_mul_f32 v[2:3], v[10:11], v[106:107]
	v_cvt_pk_bf16_f32 v0, v0, v1
	v_cvt_pk_bf16_f32 v1, v2, v3
	global_store_dwordx2 v[62:63], v[0:1], off offset:2560
	v_pk_mul_f32 v[8:9], v[28:29], v[64:65] op_sel_hi:[1,0]
	v_pk_mul_f32 v[10:11], v[30:31], v[64:65] op_sel_hi:[1,0]
	v_pk_mul_f32 v[0:1], v[8:9], v[108:109]
	v_pk_mul_f32 v[2:3], v[10:11], v[110:111]
	v_cvt_pk_bf16_f32 v0, v0, v1
	v_cvt_pk_bf16_f32 v1, v2, v3
	global_store_dwordx2 v[62:63], v[0:1], off offset:3072
	v_pk_mul_f32 v[0:1], v[4:5], v[112:113]
	v_pk_mul_f32 v[2:3], v[6:7], v[114:115]
	v_cvt_pk_bf16_f32 v0, v0, v1
	v_cvt_pk_bf16_f32 v1, v2, v3
	global_store_dwordx2 v[62:63], v[0:1], off offset:3584
	s_cbranch_scc0 .LBB0_156
